# placement: GDOWN/GOUT body shifted +12 bytes (loop head at 44 mod 64), GUP body unchanged
# baseline (speedup 1.0000x reference)
.LBB0_98:
	s_nop 0
	s_nop 0
	s_nop 0
	s_nop 0
	s_nop 0
	s_nop 0
	s_nop 0
	s_nop 0
	s_nop 0
	s_nop 0
	s_nop 0
	s_nop 0
	s_nop 0
	s_nop 0
	s_nop 0
	s_nop 0
	s_branch .LBB0_144

.LBB0_228:
	s_nop 0
	s_nop 0
	s_nop 0
	s_nop 0
	s_nop 0
	s_nop 0
	s_nop 0
	s_nop 0
	s_nop 0
	s_nop 0
	s_nop 0
	s_nop 0
	s_nop 0
	s_mov_b64 s[26:27], 0
